# barrier after the in-proj phase: non-leader arrivers issue an early L2 writeback before spinning so the XCC leader's writeback has less to flush (on v85)
# baseline (speedup 1.0000x reference)
; __device__ __forceinline__ unsigned xb_ld(unsigned* p)              { return __hip_atomic_load(p, __ATOMIC_RELAXED, __HIP_MEMORY_SCOPE_AGENT); }
; __device__ __forceinline__ unsigned xb_add(unsigned* p, unsigned v) { return __hip_atomic_fetch_add(p, v, __ATOMIC_RELAXED, __HIP_MEMORY_SCOPE_AGENT); }
; #define XB_SPIN(cond, bar) do { unsigned _sp = 0; while (cond) { __builtin_amdgcn_s_sleep(1); \
;     if ((++_sp & 255u) == 0u) { if (xb_ld(&(bar)[XB_TMO])) break; if (_sp > XB_SPIN_CAP) { atomicAdd(&(bar)[XB_TMO], 1u); break; } } } } while (0)
; __device__ __forceinline__ void xcd_barrier(const XcdBarrier& b) {
;     ...
;         const unsigned old = xb_add(&bar[XB_XSUB(b.x)], 1u);
;         const unsigned gen = old / nloc;
;         if (old + 1u == (gen + 1u) * nloc) {
;             __builtin_amdgcn_fence(__ATOMIC_RELEASE, "agent");
;             asm volatile("s_waitcnt vmcnt(0)" ::: "memory");
;             const unsigned og = xb_add(&bar[XB_TOP], 1u);
;             const unsigned tg = og / nx;
;             if (og + 1u == (tg + 1u) * nx) xb_add(&bar[XB_TOPGEN], 1u);
;             else XB_SPIN(xb_ld(&bar[XB_TOPGEN]) == tg, bar);
;             __builtin_amdgcn_fence(__ATOMIC_ACQUIRE, "agent");
;             xb_add(&bar[XB_XGEN(b.x)], 1u);
;             asm volatile("s_waitcnt vmcnt(0)" ::: "memory");
;         } else {
;             XB_SPIN(xb_ld(&bar[XB_XGEN(b.x)]) == gen, bar);
.LBB0_519:
	s_or_b64 exec, exec, s[10:11]
	v_cvt_f32_u32_e32 v4, v2
	s_waitcnt vmcnt(0)
	v_readfirstlane_b32 s0, v3
	v_sub_u32_e32 v3, 0, v2
	v_rcp_iflag_f32_e32 v4, v4
	v_add_u32_e32 v5, s0, v1
	v_mul_f32_e32 v4, 0x4f7ffffe, v4
	v_cvt_u32_f32_e32 v4, v4
	v_mul_lo_u32 v1, v3, v4
	v_mul_hi_u32 v1, v4, v1
	v_add_u32_e32 v1, v4, v1
	v_mul_hi_u32 v1, v5, v1
	v_mul_lo_u32 v3, v1, v2
	v_sub_u32_e32 v3, v5, v3
	v_add_u32_e32 v4, 1, v1
	v_cmp_ge_u32_e32 vcc, v3, v2
	s_nop 1
	v_cndmask_b32_e32 v1, v1, v4, vcc
	v_sub_u32_e32 v4, v3, v2
	v_cndmask_b32_e32 v3, v3, v4, vcc
	v_add_u32_e32 v4, 1, v1
	v_cmp_ge_u32_e32 vcc, v3, v2
	v_add_u32_e32 v3, 1, v5
	s_nop 0
	v_cndmask_b32_e32 v1, v1, v4, vcc
	v_mul_lo_u32 v4, v2, v1
	v_add_u32_e32 v2, v4, v2
	v_cmp_ne_u32_e32 vcc, v3, v2
	s_and_saveexec_b64 s[0:1], vcc
	s_xor_b64 s[6:7], exec, s[0:1]
	s_cbranch_execz .LBB0_533
	s_waitcnt lgkmcnt(0)
	buffer_wbl2 sc1
	s_nop 0
	v_mov_b32_e32 v0, 0x2000
	global_load_dword v0, v0, s[4:5] offset:1024 sc1
	s_add_u32 s22, s4, 0x2400
	s_addc_u32 s23, s5, 0
	s_waitcnt vmcnt(0)
	v_cmp_eq_u32_e32 vcc, v0, v1
	s_and_saveexec_b64 s[10:11], vcc
	s_cbranch_execz .LBB0_532
	s_add_u32 s20, s28, 0x210200
	s_addc_u32 s21, s29, 0
	s_mov_b32 s0, 1
	s_mov_b64 s[42:43], 0
	v_mov_b32_e32 v0, 0
	s_branch .LBB0_523
